# adds P3 first-epilogue gate loads widened 8B->16B (32->16 loads, reverse permlane16_swap, consumers renamed, waits re-derived) on top of the widened-store version
# speedup vs baseline: 1.0424x; 1.0010x over previous
.LBB0_288:
	s_or_b64 exec, exec, s[6:7]
	v_lshl_or_b32 v134, s50, 8, v1
	v_lshl_or_b32 v132, s48, 8, v160
	v_mov_b32_e32 v136, v134
	v_mov_b32_e32 v140, v132
	s_waitcnt vmcnt(0)
	s_barrier
	v_mbcnt_lo_u32_b32 v242, -1, 0
	v_mbcnt_hi_u32_b32 v242, -1, v242
	v_bfe_u32 v242, v242, 4, 1
	v_mul_u32_u24_e32 v242, 24, v242
	v_mov_b32_e32 v243, 0
	v_mbcnt_lo_u32_b32 v244, -1, 0
	v_mbcnt_hi_u32_b32 v244, -1, v244
	v_bfe_u32 v244, v244, 4, 1
	v_mul_u32_u24_e32 v244, 24, v244
	v_mov_b32_e32 v245, 0
	s_nop 0
	v_ashrrev_i32_e32 v141, 31, v140
	v_lshlrev_b64 v[138:139], 12, v[140:141]
	v_ashrrev_i32_e32 v137, 31, v136
	v_lshlrev_b64 v[140:141], 11, v[140:141]
	v_lshl_add_u64 v[138:139], s[76:77], 0, v[138:139]
	v_lshlrev_b64 v[136:137], 1, v[136:137]
	v_lshl_add_u64 v[140:141], s[82:83], 0, v[140:141]
	v_lshl_add_u64 v[138:139], v[138:139], 0, v[136:137]
	v_lshl_add_u64 v[136:137], v[140:141], 0, v[136:137]
	v_lshl_add_u64 v[246:247], v[138:139], 0, v[242:243]
	global_load_dwordx4 v[192:195], v[246:247], off
	global_load_dwordx4 v[196:199], v[246:247], off offset:64
	v_lshl_add_u64 v[246:247], v[138:139], 0, v[242:243]
	global_load_dwordx4 v[200:203], v[246:247], off offset:256
	global_load_dwordx4 v[204:207], v[246:247], off offset:320
	v_add_co_u32_e64 v156, s[6:7], s11, v138
	s_waitcnt vmcnt(3)
	v_permlane16_swap_b32_e32 v192, v194
	v_permlane16_swap_b32_e32 v193, v195
	v_lshlrev_b32_e32 v130, 16, v192
	v_addc_co_u32_e64 v157, s[6:7], 0, v139, s[6:7]
	v_lshl_add_u64 v[246:247], v[156:157], 0, v[242:243]
	global_load_dwordx4 v[208:211], v[246:247], off
	global_load_dwordx4 v[212:215], v[246:247], off offset:64
	v_lshl_add_u64 v[246:247], v[156:157], 0, v[242:243]
	global_load_dwordx4 v[216:219], v[246:247], off offset:256
	global_load_dwordx4 v[220:223], v[246:247], off offset:320
	s_nop 0
	v_and_b32_e32 v133, 0xffff0000, v192
	v_lshlrev_b32_e32 v135, 16, v193
	v_and_b32_e32 v140, 0xffff0000, v193
	s_waitcnt vmcnt(7)
	v_lshlrev_b32_e32 v141, 16, v194
	v_and_b32_e32 v142, 0xffff0000, v194
	v_lshlrev_b32_e32 v182, 16, v195
	v_and_b32_e32 v143, 0xffff0000, v195
	s_waitcnt vmcnt(6)
	v_permlane16_swap_b32_e32 v196, v198
	v_permlane16_swap_b32_e32 v197, v199
	v_lshlrev_b32_e32 v183, 16, v196
	v_and_b32_e32 v144, 0xffff0000, v196
	v_lshlrev_b32_e32 v184, 16, v197
	v_and_b32_e32 v145, 0xffff0000, v197
	s_waitcnt vmcnt(6)
	v_lshlrev_b32_e32 v185, 16, v198
	v_and_b32_e32 v146, 0xffff0000, v198
	v_lshlrev_b32_e32 v186, 16, v199
	v_and_b32_e32 v147, 0xffff0000, v199
	s_waitcnt vmcnt(5)
	v_permlane16_swap_b32_e32 v200, v202
	v_permlane16_swap_b32_e32 v201, v203
	v_lshlrev_b32_e32 v187, 16, v200
	v_and_b32_e32 v148, 0xffff0000, v200
	v_lshlrev_b32_e32 v188, 16, v201
	v_and_b32_e32 v149, 0xffff0000, v201
	v_mul_f32_e32 v98, v98, v130
	v_mul_f32_e32 v99, v99, v133
	v_mul_f32_e32 v100, v100, v135
	v_mul_f32_e32 v101, v101, v140
	v_mul_f32_e32 v102, v102, v141
	v_mul_f32_e32 v103, v103, v142
	v_mul_f32_e32 v104, v104, v182
	v_mul_f32_e32 v105, v105, v143
	v_mul_f32_e32 v106, v106, v183
	v_mul_f32_e32 v107, v107, v144
	v_mul_f32_e32 v108, v108, v184
	v_mul_f32_e32 v109, v109, v145
	v_mul_f32_e32 v110, v110, v185
	v_mul_f32_e32 v111, v111, v146
	v_mul_f32_e32 v112, v112, v186
	v_mul_f32_e32 v113, v113, v147
	v_mul_f32_e32 v122, v122, v187
	v_mul_f32_e32 v123, v123, v148
	v_mul_f32_e32 v124, v124, v188
	v_mul_f32_e32 v125, v125, v149
	v_cvt_pk_bf16_f32 v224, v98, v99
	v_cvt_pk_bf16_f32 v225, v100, v101
	v_cvt_pk_bf16_f32 v226, v102, v103
	v_cvt_pk_bf16_f32 v227, v104, v105
	v_cvt_pk_bf16_f32 v228, v106, v107
	v_cvt_pk_bf16_f32 v229, v108, v109
	v_cvt_pk_bf16_f32 v230, v110, v111
	v_cvt_pk_bf16_f32 v231, v112, v113
	v_cvt_pk_bf16_f32 v232, v122, v123
	v_cvt_pk_bf16_f32 v233, v124, v125
	s_nop 1
	v_permlane16_swap_b32_e32 v224, v226
	v_permlane16_swap_b32_e32 v225, v227
	v_permlane16_swap_b32_e32 v228, v230
	v_permlane16_swap_b32_e32 v229, v231
	v_lshl_add_u64 v[240:241], v[136:137], 0, v[244:245]
	global_store_dwordx4 v[240:241], v[224:227], off
	global_store_dwordx4 v[240:241], v[228:231], off offset:64
	s_waitcnt vmcnt(6)
	v_permlane16_swap_b32_e32 v204, v206
	v_permlane16_swap_b32_e32 v205, v207
	v_lshlrev_b32_e32 v98, 16, v204
	v_and_b32_e32 v99, 0xffff0000, v204
	v_lshlrev_b32_e32 v100, 16, v205
	v_and_b32_e32 v101, 0xffff0000, v205
	v_mul_f32_e32 v98, v118, v98
	v_mul_f32_e32 v99, v119, v99
	v_mul_f32_e32 v100, v120, v100
	v_mul_f32_e32 v101, v121, v101
	v_cvt_pk_bf16_f32 v236, v98, v99
	v_cvt_pk_bf16_f32 v237, v100, v101
	s_waitcnt vmcnt(6)
	v_lshlrev_b32_e32 v98, 16, v206
	v_and_b32_e32 v99, 0xffff0000, v206
	v_lshlrev_b32_e32 v100, 16, v207
	v_and_b32_e32 v101, 0xffff0000, v207
	v_mul_f32_e32 v98, v114, v98
	v_mul_f32_e32 v99, v115, v99
	v_mul_f32_e32 v100, v116, v100
	v_mul_f32_e32 v101, v117, v101
	v_cvt_pk_bf16_f32 v238, v98, v99
	v_cvt_pk_bf16_f32 v239, v100, v101
	s_waitcnt vmcnt(5)
	v_permlane16_swap_b32_e32 v208, v210
	v_permlane16_swap_b32_e32 v209, v211
	v_lshlrev_b32_e32 v98, 16, v208
	v_mul_f32_e32 v94, v94, v98
	v_and_b32_e32 v98, 0xffff0000, v208
	v_mul_f32_e32 v95, v95, v98
	v_lshlrev_b32_e32 v98, 16, v209
	v_mul_f32_e32 v96, v96, v98
	v_and_b32_e32 v98, 0xffff0000, v209
	v_mul_f32_e32 v97, v97, v98
	v_cvt_pk_bf16_f32 v224, v94, v95
	v_cvt_pk_bf16_f32 v225, v96, v97
	v_add_co_u32_e64 v96, s[6:7], s61, v136
	v_lshlrev_b32_e32 v189, 16, v202
	s_nop 0
	v_addc_co_u32_e64 v97, s[6:7], 0, v137, s[6:7]
	s_waitcnt vmcnt(5)
	v_lshlrev_b32_e32 v94, 16, v210
	v_mul_f32_e32 v82, v82, v94
	v_and_b32_e32 v94, 0xffff0000, v210
	v_mul_f32_e32 v83, v83, v94
	v_lshlrev_b32_e32 v94, 16, v211
	v_mul_f32_e32 v84, v84, v94
	v_and_b32_e32 v94, 0xffff0000, v211
	v_mul_f32_e32 v85, v85, v94
	v_cvt_pk_bf16_f32 v226, v82, v83
	v_cvt_pk_bf16_f32 v227, v84, v85
	s_waitcnt vmcnt(4)
	v_permlane16_swap_b32_e32 v212, v214
	v_permlane16_swap_b32_e32 v213, v215
	v_lshlrev_b32_e32 v82, 16, v212
	v_mul_f32_e32 v74, v74, v82
	v_and_b32_e32 v82, 0xffff0000, v212
	v_mul_f32_e32 v75, v75, v82
	v_lshlrev_b32_e32 v82, 16, v213
	v_mul_f32_e32 v76, v76, v82
	v_and_b32_e32 v82, 0xffff0000, v213
	v_mul_f32_e32 v77, v77, v82
	v_cvt_pk_bf16_f32 v228, v74, v75
	v_cvt_pk_bf16_f32 v229, v76, v77
	s_waitcnt vmcnt(4)
	v_lshlrev_b32_e32 v74, 16, v214
	v_mul_f32_e32 v66, v66, v74
	v_and_b32_e32 v74, 0xffff0000, v214
	v_mul_f32_e32 v67, v67, v74
	v_lshlrev_b32_e32 v74, 16, v215
	v_mul_f32_e32 v68, v68, v74
	v_and_b32_e32 v74, 0xffff0000, v215
	v_mul_f32_e32 v69, v69, v74
	v_cvt_pk_bf16_f32 v230, v66, v67
	v_cvt_pk_bf16_f32 v231, v68, v69
	s_nop 1
	v_permlane16_swap_b32_e32 v224, v226
	v_permlane16_swap_b32_e32 v225, v227
	v_permlane16_swap_b32_e32 v228, v230
	v_permlane16_swap_b32_e32 v229, v231
	v_lshl_add_u64 v[240:241], v[96:97], 0, v[244:245]
	global_store_dwordx4 v[240:241], v[224:227], off
	global_store_dwordx4 v[240:241], v[228:231], off offset:64
	s_waitcnt vmcnt(5)
	v_permlane16_swap_b32_e32 v216, v218
	v_permlane16_swap_b32_e32 v217, v219
	v_lshlrev_b32_e32 v66, 16, v216
	v_and_b32_e32 v67, 0xffff0000, v216
	v_lshlrev_b32_e32 v68, 16, v217
	v_and_b32_e32 v69, 0xffff0000, v217
	v_mul_f32_e32 v66, v90, v66
	v_mul_f32_e32 v67, v91, v67
	v_mul_f32_e32 v68, v92, v68
	v_mul_f32_e32 v69, v93, v69
	v_cvt_pk_bf16_f32 v224, v66, v67
	v_cvt_pk_bf16_f32 v225, v68, v69
	s_waitcnt vmcnt(5)
	v_lshlrev_b32_e32 v66, 16, v218
	v_and_b32_e32 v67, 0xffff0000, v218
	v_lshlrev_b32_e32 v68, 16, v219
	v_and_b32_e32 v69, 0xffff0000, v219
	v_mul_f32_e32 v66, v86, v66
	v_mul_f32_e32 v67, v87, v67
	v_mul_f32_e32 v68, v88, v68
	v_mul_f32_e32 v69, v89, v69
	v_cvt_pk_bf16_f32 v226, v66, v67
	v_cvt_pk_bf16_f32 v227, v68, v69
	s_waitcnt vmcnt(4)
	v_permlane16_swap_b32_e32 v220, v222
	v_permlane16_swap_b32_e32 v221, v223
	v_lshlrev_b32_e32 v66, 16, v220
	v_and_b32_e32 v67, 0xffff0000, v220
	v_lshlrev_b32_e32 v68, 16, v221
	v_and_b32_e32 v69, 0xffff0000, v221
	v_mul_f32_e32 v66, v78, v66
	v_mul_f32_e32 v67, v79, v67
	v_mul_f32_e32 v68, v80, v68
	v_mul_f32_e32 v69, v81, v69
	v_cvt_pk_bf16_f32 v228, v66, v67
	v_cvt_pk_bf16_f32 v229, v68, v69
	v_and_b32_e32 v150, 0xffff0000, v202
	v_lshlrev_b32_e32 v190, 16, v203
	v_and_b32_e32 v151, 0xffff0000, v203
	s_waitcnt vmcnt(4)
	v_lshlrev_b32_e32 v66, 16, v222
	v_and_b32_e32 v67, 0xffff0000, v222
	v_lshlrev_b32_e32 v68, 16, v223
	v_and_b32_e32 v69, 0xffff0000, v223
	v_mul_f32_e32 v126, v126, v189
	v_mul_f32_e32 v127, v127, v150
	v_mul_f32_e32 v128, v128, v190
	v_mul_f32_e32 v129, v129, v151
	v_mul_f32_e32 v66, v70, v66
	v_mul_f32_e32 v67, v71, v67
	v_mul_f32_e32 v68, v72, v68
	v_mul_f32_e32 v69, v73, v69
	v_cvt_pk_bf16_f32 v234, v126, v127
	v_cvt_pk_bf16_f32 v235, v128, v129
	v_cvt_pk_bf16_f32 v230, v66, v67
	v_cvt_pk_bf16_f32 v231, v68, v69
	s_nop 1
	v_permlane16_swap_b32_e32 v232, v234
	v_permlane16_swap_b32_e32 v233, v235
	v_permlane16_swap_b32_e32 v236, v238
	v_permlane16_swap_b32_e32 v237, v239
	v_lshl_add_u64 v[240:241], v[136:137], 0, v[244:245]
	global_store_dwordx4 v[240:241], v[232:235], off offset:256
	global_store_dwordx4 v[240:241], v[236:239], off offset:320
	s_nop 1
	v_permlane16_swap_b32_e32 v224, v226
	v_permlane16_swap_b32_e32 v225, v227
	v_permlane16_swap_b32_e32 v228, v230
	v_permlane16_swap_b32_e32 v229, v231
	v_lshl_add_u64 v[240:241], v[96:97], 0, v[244:245]
	global_store_dwordx4 v[240:241], v[224:227], off offset:256
	global_store_dwordx4 v[240:241], v[228:231], off offset:320
	v_add_co_u32_e64 v66, s[6:7], s62, v138
	s_mov_b32 s0, s48
	s_nop 0
	v_addc_co_u32_e64 v67, s[6:7], 0, v139, s[6:7]
	v_lshl_add_u64 v[246:247], v[66:67], 0, v[242:243]
	global_load_dwordx4 v[192:195], v[246:247], off
	global_load_dwordx4 v[196:199], v[246:247], off offset:64
	v_lshl_add_u64 v[246:247], v[66:67], 0, v[242:243]
	global_load_dwordx4 v[200:203], v[246:247], off offset:256
	global_load_dwordx4 v[204:207], v[246:247], off offset:320
	v_add_co_u32_e64 v80, s[6:7], s63, v138
	s_waitcnt vmcnt(3)
	v_permlane16_swap_b32_e32 v192, v194
	v_permlane16_swap_b32_e32 v193, v195
	v_lshlrev_b32_e32 v100, 16, v192
	v_addc_co_u32_e64 v81, s[6:7], 0, v139, s[6:7]
	s_nop 0
	v_lshl_add_u64 v[246:247], v[80:81], 0, v[242:243]
	global_load_dwordx4 v[208:211], v[246:247], off
	global_load_dwordx4 v[212:215], v[246:247], off offset:64
	v_lshl_add_u64 v[246:247], v[80:81], 0, v[242:243]
	global_load_dwordx4 v[216:219], v[246:247], off offset:256
	global_load_dwordx4 v[220:223], v[246:247], off offset:320
	s_nop 0
	v_and_b32_e32 v68, 0xffff0000, v192
	v_lshlrev_b32_e32 v101, 16, v193
	v_and_b32_e32 v69, 0xffff0000, v193
	s_waitcnt vmcnt(7)
	v_lshlrev_b32_e32 v102, 16, v194
	v_and_b32_e32 v70, 0xffff0000, v194
	v_add_co_u32_e64 v84, s[6:7], s64, v136
	v_lshlrev_b32_e32 v103, 16, v195
	v_and_b32_e32 v71, 0xffff0000, v195
	s_waitcnt vmcnt(6)
	v_permlane16_swap_b32_e32 v196, v198
	v_permlane16_swap_b32_e32 v197, v199
	v_lshlrev_b32_e32 v104, 16, v196
	v_and_b32_e32 v72, 0xffff0000, v196
	v_lshlrev_b32_e32 v105, 16, v197
	v_and_b32_e32 v73, 0xffff0000, v197
	s_waitcnt vmcnt(6)
	v_lshlrev_b32_e32 v106, 16, v198
	v_and_b32_e32 v74, 0xffff0000, v198
	v_lshlrev_b32_e32 v107, 16, v199
	v_and_b32_e32 v75, 0xffff0000, v199
	s_waitcnt vmcnt(5)
	v_permlane16_swap_b32_e32 v200, v202
	v_permlane16_swap_b32_e32 v201, v203
	v_lshlrev_b32_e32 v108, 16, v200
	v_and_b32_e32 v76, 0xffff0000, v200
	v_lshlrev_b32_e32 v109, 16, v201
	v_and_b32_e32 v77, 0xffff0000, v201
	v_mul_f32_e32 v38, v38, v100
	v_mul_f32_e32 v39, v39, v68
	v_mul_f32_e32 v40, v40, v101
	v_mul_f32_e32 v41, v41, v69
	v_mul_f32_e32 v42, v42, v102
	v_mul_f32_e32 v43, v43, v70
	v_addc_co_u32_e64 v85, s[6:7], 0, v137, s[6:7]
	v_mul_f32_e32 v44, v44, v103
	v_mul_f32_e32 v45, v45, v71
	v_mul_f32_e32 v46, v46, v104
	v_mul_f32_e32 v47, v47, v72
	v_mul_f32_e32 v48, v48, v105
	v_mul_f32_e32 v49, v49, v73
	v_mul_f32_e32 v50, v50, v106
	v_mul_f32_e32 v51, v51, v74
	v_mul_f32_e32 v52, v52, v107
	v_mul_f32_e32 v53, v53, v75
	v_mul_f32_e32 v62, v62, v108
	v_mul_f32_e32 v63, v63, v76
	v_mul_f32_e32 v64, v64, v109
	v_mul_f32_e32 v65, v65, v77
	v_cvt_pk_bf16_f32 v232, v38, v39
	v_cvt_pk_bf16_f32 v233, v40, v41
	v_cvt_pk_bf16_f32 v234, v42, v43
	s_waitcnt vmcnt(5)
	v_lshlrev_b32_e32 v110, 16, v202
	v_cvt_pk_bf16_f32 v235, v44, v45
	v_cvt_pk_bf16_f32 v236, v46, v47
	v_cvt_pk_bf16_f32 v237, v48, v49
	v_cvt_pk_bf16_f32 v238, v50, v51
	v_cvt_pk_bf16_f32 v239, v52, v53
	v_cvt_pk_bf16_f32 v224, v62, v63
	v_cvt_pk_bf16_f32 v225, v64, v65
	s_nop 1
	v_permlane16_swap_b32_e32 v232, v234
	v_permlane16_swap_b32_e32 v233, v235
	v_permlane16_swap_b32_e32 v236, v238
	v_permlane16_swap_b32_e32 v237, v239
	v_lshl_add_u64 v[240:241], v[84:85], 0, v[244:245]
	global_store_dwordx4 v[240:241], v[232:235], off
	global_store_dwordx4 v[240:241], v[236:239], off offset:64
	v_and_b32_e32 v38, 0xffff0000, v202
	v_lshlrev_b32_e32 v39, 16, v203
	v_and_b32_e32 v40, 0xffff0000, v203
	v_mul_f32_e32 v58, v58, v110
	v_mul_f32_e32 v38, v59, v38
	v_mul_f32_e32 v39, v60, v39
	v_mul_f32_e32 v40, v61, v40
	v_cvt_pk_bf16_f32 v226, v58, v38
	v_cvt_pk_bf16_f32 v227, v39, v40
	s_waitcnt vmcnt(6)
	v_permlane16_swap_b32_e32 v204, v206
	v_permlane16_swap_b32_e32 v205, v207
	v_lshlrev_b32_e32 v38, 16, v204
	v_and_b32_e32 v39, 0xffff0000, v204
	v_lshlrev_b32_e32 v40, 16, v205
	v_and_b32_e32 v41, 0xffff0000, v205
	v_mul_f32_e32 v38, v54, v38
	v_mul_f32_e32 v39, v55, v39
	v_mul_f32_e32 v40, v56, v40
	v_mul_f32_e32 v41, v57, v41
	v_cvt_pk_bf16_f32 v228, v38, v39
	v_cvt_pk_bf16_f32 v229, v40, v41
	s_waitcnt vmcnt(6)
	v_lshlrev_b32_e32 v38, 16, v206
	v_mul_f32_e32 v34, v34, v38
	v_and_b32_e32 v38, 0xffff0000, v206
	v_mul_f32_e32 v35, v35, v38
	v_lshlrev_b32_e32 v38, 16, v207
	v_mul_f32_e32 v36, v36, v38
	v_and_b32_e32 v38, 0xffff0000, v207
	v_mul_f32_e32 v37, v37, v38
	v_cvt_pk_bf16_f32 v230, v34, v35
	v_cvt_pk_bf16_f32 v231, v36, v37
	s_nop 1
	v_permlane16_swap_b32_e32 v224, v226
	v_permlane16_swap_b32_e32 v225, v227
	v_permlane16_swap_b32_e32 v228, v230
	v_permlane16_swap_b32_e32 v229, v231
	v_lshl_add_u64 v[240:241], v[84:85], 0, v[244:245]
	global_store_dwordx4 v[240:241], v[224:227], off offset:256
	global_store_dwordx4 v[240:241], v[228:231], off offset:320
	s_waitcnt vmcnt(7)
	v_permlane16_swap_b32_e32 v208, v210
	v_permlane16_swap_b32_e32 v209, v211
	v_lshlrev_b32_e32 v34, 16, v208
	v_mul_f32_e32 v30, v30, v34
	v_and_b32_e32 v34, 0xffff0000, v208
	v_mul_f32_e32 v31, v31, v34
	v_lshlrev_b32_e32 v34, 16, v209
	v_mul_f32_e32 v32, v32, v34
	v_and_b32_e32 v34, 0xffff0000, v209
	v_mul_f32_e32 v33, v33, v34
	v_cvt_pk_bf16_f32 v232, v30, v31
	v_cvt_pk_bf16_f32 v233, v32, v33
	v_add_co_u32_e64 v32, s[6:7], s65, v136
	s_nop 1
	v_addc_co_u32_e64 v33, s[6:7], 0, v137, s[6:7]
	s_waitcnt vmcnt(7)
	v_lshlrev_b32_e32 v30, 16, v210
	v_mul_f32_e32 v22, v22, v30
	v_and_b32_e32 v30, 0xffff0000, v210
	v_mul_f32_e32 v23, v23, v30
	v_lshlrev_b32_e32 v30, 16, v211
	v_mul_f32_e32 v24, v24, v30
	v_and_b32_e32 v30, 0xffff0000, v211
	v_mul_f32_e32 v25, v25, v30
	v_cvt_pk_bf16_f32 v234, v22, v23
	v_cvt_pk_bf16_f32 v235, v24, v25
	s_waitcnt vmcnt(6)
	v_permlane16_swap_b32_e32 v212, v214
	v_permlane16_swap_b32_e32 v213, v215
	v_lshlrev_b32_e32 v22, 16, v212
	v_mul_f32_e32 v14, v14, v22
	v_and_b32_e32 v22, 0xffff0000, v212
	v_mul_f32_e32 v15, v15, v22
	v_lshlrev_b32_e32 v22, 16, v213
	v_mul_f32_e32 v16, v16, v22
	v_and_b32_e32 v22, 0xffff0000, v213
	v_mul_f32_e32 v17, v17, v22
	v_cvt_pk_bf16_f32 v236, v14, v15
	v_cvt_pk_bf16_f32 v237, v16, v17
	s_waitcnt vmcnt(6)
	v_lshlrev_b32_e32 v14, 16, v214
	v_mul_f32_e32 v6, v6, v14
	v_and_b32_e32 v14, 0xffff0000, v214
	v_mul_f32_e32 v7, v7, v14
	v_lshlrev_b32_e32 v14, 16, v215
	v_mul_f32_e32 v8, v8, v14
	v_and_b32_e32 v14, 0xffff0000, v215
	v_mul_f32_e32 v9, v9, v14
	v_cvt_pk_bf16_f32 v238, v6, v7
	v_cvt_pk_bf16_f32 v239, v8, v9
	s_nop 1
	v_permlane16_swap_b32_e32 v232, v234
	v_permlane16_swap_b32_e32 v233, v235
	v_permlane16_swap_b32_e32 v236, v238
	v_permlane16_swap_b32_e32 v237, v239
	v_lshl_add_u64 v[240:241], v[32:33], 0, v[244:245]
	global_store_dwordx4 v[240:241], v[232:235], off
	global_store_dwordx4 v[240:241], v[236:239], off offset:64
	s_waitcnt vmcnt(7)
	v_permlane16_swap_b32_e32 v216, v218
	v_permlane16_swap_b32_e32 v217, v219
	v_lshlrev_b32_e32 v6, 16, v216
	v_and_b32_e32 v7, 0xffff0000, v216
	v_lshlrev_b32_e32 v8, 16, v217
	v_and_b32_e32 v9, 0xffff0000, v217
	v_mul_f32_e32 v6, v26, v6
	v_mul_f32_e32 v7, v27, v7
	v_mul_f32_e32 v8, v28, v8
	v_mul_f32_e32 v9, v29, v9
	v_cvt_pk_bf16_f32 v224, v6, v7
	v_cvt_pk_bf16_f32 v225, v8, v9
	s_waitcnt vmcnt(7)
	v_lshlrev_b32_e32 v6, 16, v218
	v_and_b32_e32 v7, 0xffff0000, v218
	v_lshlrev_b32_e32 v8, 16, v219
	v_and_b32_e32 v9, 0xffff0000, v219
	v_mul_f32_e32 v6, v18, v6
	v_mul_f32_e32 v7, v19, v7
	v_mul_f32_e32 v8, v20, v8
	v_mul_f32_e32 v9, v21, v9
	v_cvt_pk_bf16_f32 v226, v6, v7
	v_cvt_pk_bf16_f32 v227, v8, v9
	s_waitcnt vmcnt(6)
	v_permlane16_swap_b32_e32 v220, v222
	v_permlane16_swap_b32_e32 v221, v223
	v_lshlrev_b32_e32 v6, 16, v220
	v_and_b32_e32 v7, 0xffff0000, v220
	v_lshlrev_b32_e32 v8, 16, v221
	v_and_b32_e32 v9, 0xffff0000, v221
	v_mul_f32_e32 v6, v10, v6
	v_mul_f32_e32 v7, v11, v7
	v_mul_f32_e32 v8, v12, v8
	v_mul_f32_e32 v9, v13, v9
	v_cvt_pk_bf16_f32 v228, v6, v7
	v_cvt_pk_bf16_f32 v229, v8, v9
	s_waitcnt vmcnt(6)
	v_lshlrev_b32_e32 v6, 16, v222
	v_mul_f32_e32 v2, v2, v6
	v_and_b32_e32 v6, 0xffff0000, v222
	v_mul_f32_e32 v3, v3, v6
	v_lshlrev_b32_e32 v6, 16, v223
	v_mul_f32_e32 v4, v4, v6
	v_and_b32_e32 v6, 0xffff0000, v223
	v_mul_f32_e32 v5, v5, v6
	v_cvt_pk_bf16_f32 v230, v2, v3
	v_cvt_pk_bf16_f32 v231, v4, v5
	s_nop 1
	v_permlane16_swap_b32_e32 v224, v226
	v_permlane16_swap_b32_e32 v225, v227
	v_permlane16_swap_b32_e32 v228, v230
	v_permlane16_swap_b32_e32 v229, v231
	v_lshl_add_u64 v[240:241], v[32:33], 0, v[244:245]
	global_store_dwordx4 v[240:241], v[224:227], off offset:256
	global_store_dwordx4 v[240:241], v[228:231], off offset:320
	v_mov_b32_e32 v2, v0
	s_ashr_i32 s51, s50, 31
	v_lshlrev_b32_e32 v3, 4, v2
	v_bfe_i32 v2, v2, 27, 1
	v_lshrrev_b32_e32 v2, 22, v2
	v_add_u32_e32 v2, v3, v2
	v_ashrrev_i32_e32 v10, 10, v2
	v_mul_i32_i24_e32 v2, 0x400, v10
	v_sub_u32_e32 v2, v3, v2
	v_add_u32_e32 v4, 0x2000, v3
	v_lshrrev_b32_e32 v3, 4, v2
	v_bitop3_b32 v2, v3, v2, 32 bitop3:0x6c
	v_ashrrev_i32_e32 v5, 31, v2
	v_lshrrev_b32_e32 v5, 26, v5
	v_add_u32_e32 v5, v2, v5
	v_ashrrev_i32_e32 v12, 6, v5
	v_and_b32_e32 v5, 0xc0, v5
	v_sub_u32_e32 v2, v2, v5
	v_ashrrev_i16_sdwa v14, v169, sext(v2) dst_sel:DWORD dst_unused:UNUSED_PAD src0_sel:DWORD src1_sel:BYTE_0
	v_ashrrev_i32_e32 v2, 31, v4
	v_lshrrev_b32_e32 v2, 22, v2
	v_add_u32_e32 v2, v4, v2
	v_ashrrev_i32_e32 v11, 10, v2
	v_mul_i32_i24_e32 v2, 0x400, v11
	v_sub_u32_e32 v2, v4, v2
	v_lshrrev_b32_e32 v4, 4, v2
	v_bitop3_b32 v2, v4, v2, 32 bitop3:0x6c
	s_lshl_b64 s[50:51], s[50:51], 19
	v_ashrrev_i32_e32 v5, 31, v2
	s_add_u32 s6, s38, s50
	v_lshrrev_b32_e32 v5, 26, v5
	s_addc_u32 s7, s39, s51
	s_ashr_i32 s1, s0, 31
	v_lshlrev_b32_e32 v3, 3, v10
	v_add_u32_e32 v5, v2, v5
	s_lshl_b64 s[54:55], s[0:1], 19
	v_and_b32_e32 v3, 0x3ffff0, v3
	v_lshlrev_b32_e32 v6, 5, v10
	v_lshlrev_b32_e32 v4, 3, v11
	v_ashrrev_i32_e32 v15, 6, v5
	v_and_b32_e32 v5, 0xc0, v5
	s_add_u32 s56, s80, s54
	v_readfirstlane_b32 s0, v0
	v_add_u32_e32 v3, v12, v3
	v_and_b32_e32 v13, 32, v6
	v_and_b32_e32 v4, 0x3ffff0, v4
	v_lshlrev_b32_e32 v6, 5, v11
	v_sub_u32_e32 v2, v2, v5
	s_addc_u32 s57, s81, s55
	s_lshl_b32 s0, s0, 4
	v_add_u32_e32 v4, v15, v4
	v_and_b32_e32 v16, 32, v6
	v_ashrrev_i16_sdwa v17, v169, sext(v2) dst_sel:DWORD dst_unused:UNUSED_PAD src0_sel:DWORD src1_sel:BYTE_0
	v_lshl_or_b32 v2, v3, 10, v13
	v_lshl_or_b32 v3, v4, 10, v16
	s_and_b32 s49, s0, 0xfffffc00
	v_add_u32_sdwa v130, v2, sext(v14) dst_sel:DWORD dst_unused:UNUSED_PAD src0_sel:DWORD src1_sel:WORD_0
	v_add_u32_sdwa v136, v3, sext(v17) dst_sel:DWORD dst_unused:UNUSED_PAD src0_sel:DWORD src1_sel:WORD_0
	v_lshlrev_b64 v[18:19], 1, v[130:131]
	s_add_i32 s67, s49, 0x10000
	v_mov_b32_e32 v137, v131
	v_lshl_add_u64 v[2:3], s[56:57], 0, v[18:19]
	s_mov_b32 m0, s67
	v_lshlrev_b64 v[20:21], 1, v[136:137]
	s_add_i32 s68, s49, 0x12000
	global_load_lds_dwordx4 v[2:3], off
	v_lshl_add_u64 v[6:7], s[56:57], 0, v[20:21]
	s_mov_b32 m0, s68
	s_add_i32 s69, s49, 0x2000
	global_load_lds_dwordx4 v[6:7], off
	v_lshl_add_u64 v[8:9], s[6:7], 0, v[18:19]
	s_mov_b32 m0, s49
	s_add_u32 s0, s56, 0x40000
	global_load_lds_dwordx4 v[8:9], off
	v_lshl_add_u64 v[4:5], s[6:7], 0, v[20:21]
	s_mov_b32 m0, s69
	s_addc_u32 s1, s57, 0
	s_add_i32 s70, s49, 0x14000
	global_load_lds_dwordx4 v[4:5], off
	v_lshl_add_u64 v[22:23], s[0:1], 0, v[18:19]
	s_mov_b32 m0, s70
	s_add_i32 s71, s49, 0x16000
	global_load_lds_dwordx4 v[22:23], off
	v_lshl_add_u64 v[22:23], s[0:1], 0, v[20:21]
	s_add_u32 s0, s6, 0x40000
	s_mov_b32 m0, s71
	s_addc_u32 s1, s7, 0
	s_add_i32 s72, s49, 0x4000
	global_load_lds_dwordx4 v[22:23], off
	v_lshl_add_u64 v[18:19], s[0:1], 0, v[18:19]
	s_mov_b32 m0, s72
	s_add_i32 s73, s49, 0x6000
	global_load_lds_dwordx4 v[18:19], off
	v_lshl_add_u64 v[18:19], s[0:1], 0, v[20:21]
	s_mov_b32 m0, s73
	s_nop 0
	global_load_lds_dwordx4 v[18:19], off
	s_and_saveexec_b64 s[58:59], vcc
	s_cbranch_execz .LBB0_290
	s_barrier
